# stacked instruction-count reductions on v019: out-proj loop saddr loads, LDS fragment-read bases hoisted out of in-proj/FF1 loops, relu max folding in FF1 epilogue
# speedup vs baseline: 1.0128x; 1.0046x over previous
; #define PG8_STAGE(bufoff, gbase, voff) do { _Pragma("unroll") for (int _i = 0; _i < 2; ++_i) \
;         __builtin_amdgcn_global_load_lds((const unsigned*)((const char*)(gbase) + (voff)[_i]), (LAS unsigned*)(lds + (bufoff) + ldsw + _i * 8192), 16, 0, 0); } while (0)
; #define PG8_LDA(dst, b, h) do { _Pragma("unroll") for (int m = 0; m < 4; ++m) _Pragma("unroll") for (int k = 0; k < 2; ++k) dst[m][k] = *(const LAS bf16x8*)(lds + PG8_SA(b, h) + aoff + m * 2048 + k * 1024); } while (0)
; #define PG8_LDB(dst, b, h) do { _Pragma("unroll") for (int n = 0; n < 2; ++n) _Pragma("unroll") for (int k = 0; k < 2; ++k) dst[n][k] = *(const LAS bf16x8*)(lds + PG8_SB(b, h) + boff + n * 2048 + k * 1024); } while (0)
; #define PG8_MMA(ai, bj, At, Bt) do { __builtin_amdgcn_s_setprio(1); _Pragma("unroll") for (int m = 0; m < 4; ++m) _Pragma("unroll") for (int n = 0; n < 2; ++n) _Pragma("unroll") for (int k = 0; k < 2; ++k) \
;         acc[ai][bj][m][n] = __builtin_amdgcn_mfma_f32_16x16x32_bf16(Bt[n][k], At[m][k], acc[ai][bj][m][n], 0, 0, 0); __builtin_amdgcn_s_setprio(0); } while (0)
; #define PG8_WAIT_V(n) asm volatile("s_waitcnt vmcnt(" #n ")" ::: "memory")
; #define PG8_WAIT_L(n) asm volatile("s_waitcnt lgkmcnt(" #n ")" ::: "memory")
; #define PG8_BAR __builtin_amdgcn_s_barrier()
; #define PG8_SCHED __builtin_amdgcn_sched_barrier(0)
; template <class Epi, class Sched>
; __device__ __forceinline__ void gemm_phase(LAS unsigned char* lds, const Gemm g, const Sched& S, const Epi& E) {
;     ...
;             PG8_LDB(B0, 0, 0); PG8_SCHED; PG8_LDA(At, 0, 0); PG8_STAGE(PG8_SA(1, 1), a1 + hstep, voffA);
;             PG8_WAIT_L(8); PG8_BAR; PG8_WAIT_L(0); PG8_MMA(0, 0, At, B0); PG8_BAR; PG8_SCHED;
;             PG8_LDB(B1, 0, 1); PG8_STAGE(PG8_SB(0, 0), b2, voffB);
;             PG8_BAR; PG8_WAIT_L(0); PG8_MMA(0, 1, At, B1); PG8_BAR;
;             PG8_LDA(At, 0, 1); PG8_STAGE(PG8_SA(0, 0), a2, voffA);
;             PG8_BAR; PG8_WAIT_L(0); PG8_MMA(1, 0, At, B0); PG8_BAR; PG8_SCHED;
;             PG8_STAGE(PG8_SB(0, 1), b2 + hstep, voffB);
;             PG8_WAIT_V(6); PG8_BAR; PG8_MMA(1, 1, At, B1); PG8_BAR;
.LBB0_1279:
	s_nop 0
	ds_read_b128 v[146:149], v210
	ds_read_b128 v[150:153], v210 offset:1024
	ds_read_b128 v[154:157], v210 offset:2048
	ds_read_b128 v[158:161], v210 offset:3072
	s_add_u32 s22, s20, 0xfff80080
	s_addc_u32 s23, s21, -1
	s_cmp_eq_u32 s43, 28
	s_cselect_b32 s25, s3, s23
	s_cselect_b32 s24, s11, s22
	s_cselect_b32 s23, s9, s42
	s_cselect_b32 s22, s40, s41
	s_add_i32 m0, s17, 0xc000
	ds_read_b128 v[162:165], v145
	ds_read_b128 v[166:169], v145 offset:1024
	ds_read_b128 v[170:173], v145 offset:2048
	ds_read_b128 v[174:177], v145 offset:3072
	ds_read_b128 v[178:181], v145 offset:4096
	ds_read_b128 v[182:185], v145 offset:5120
	ds_read_b128 v[186:189], v145 offset:6144
	ds_read_b128 v[190:193], v145 offset:7168
	global_load_lds_dwordx4 v136, s[20:21]
	s_add_i32 m0, s17, 0xe000
	s_nop 0
	global_load_lds_dwordx4 v138, s[20:21]
	s_waitcnt lgkmcnt(8)
	s_barrier
	s_waitcnt lgkmcnt(0)
	v_mfma_f32_16x16x32_bf16 v[126:129], v[146:149], v[162:165], v[126:129]
	v_mfma_f32_16x16x32_bf16 v[122:125], v[154:157], v[162:165], v[122:125]
	v_mfma_f32_16x16x32_bf16 v[110:113], v[146:149], v[170:173], v[110:113]
	v_mfma_f32_16x16x32_bf16 v[106:109], v[154:157], v[170:173], v[106:109]
	v_mfma_f32_16x16x32_bf16 v[94:97], v[146:149], v[178:181], v[94:97]
	v_mfma_f32_16x16x32_bf16 v[90:93], v[154:157], v[178:181], v[90:93]
	v_mfma_f32_16x16x32_bf16 v[78:81], v[146:149], v[186:189], v[78:81]
	v_mfma_f32_16x16x32_bf16 v[74:77], v[154:157], v[186:189], v[74:77]
	v_mfma_f32_16x16x32_bf16 v[126:129], v[150:153], v[166:169], v[126:129]
	v_mfma_f32_16x16x32_bf16 v[122:125], v[158:161], v[166:169], v[122:125]
	v_mfma_f32_16x16x32_bf16 v[110:113], v[150:153], v[174:177], v[110:113]
	v_mfma_f32_16x16x32_bf16 v[106:109], v[158:161], v[174:177], v[106:109]
	v_mfma_f32_16x16x32_bf16 v[94:97], v[150:153], v[182:185], v[94:97]
	v_mfma_f32_16x16x32_bf16 v[90:93], v[158:161], v[182:185], v[90:93]
	v_mfma_f32_16x16x32_bf16 v[78:81], v[150:153], v[190:193], v[78:81]
	v_mfma_f32_16x16x32_bf16 v[74:77], v[158:161], v[190:193], v[74:77]
	s_barrier
	s_add_i32 s46, 0, 0x14000
	s_add_i32 s44, s47, s30
	ds_read_b128 v[194:197], v211
	ds_read_b128 v[198:201], v211 offset:1024
	ds_read_b128 v[202:205], v211 offset:2048
	ds_read_b128 v[206:209], v211 offset:3072
	s_mov_b32 m0, s44
	s_nop 0
	global_load_lds_dwordx4 v0, s[22:23]
	s_add_i32 m0, s44, 0x2000
	s_nop 0
	global_load_lds_dwordx4 v130, s[22:23]
	s_barrier
	s_waitcnt lgkmcnt(0)
	v_mfma_f32_16x16x32_bf16 v[118:121], v[194:197], v[162:165], v[118:121]
	v_mfma_f32_16x16x32_bf16 v[114:117], v[202:205], v[162:165], v[114:117]
	v_mfma_f32_16x16x32_bf16 v[102:105], v[194:197], v[170:173], v[102:105]
	v_mfma_f32_16x16x32_bf16 v[98:101], v[202:205], v[170:173], v[98:101]
	v_mfma_f32_16x16x32_bf16 v[86:89], v[194:197], v[178:181], v[86:89]
	v_mfma_f32_16x16x32_bf16 v[82:85], v[202:205], v[178:181], v[82:85]
	v_mfma_f32_16x16x32_bf16 v[70:73], v[194:197], v[186:189], v[70:73]
	v_mfma_f32_16x16x32_bf16 v[66:69], v[202:205], v[186:189], v[66:69]
	v_mfma_f32_16x16x32_bf16 v[118:121], v[198:201], v[166:169], v[118:121]
	v_mfma_f32_16x16x32_bf16 v[114:117], v[206:209], v[166:169], v[114:117]
	v_mfma_f32_16x16x32_bf16 v[102:105], v[198:201], v[174:177], v[102:105]
	v_mfma_f32_16x16x32_bf16 v[98:101], v[206:209], v[174:177], v[98:101]
	v_mfma_f32_16x16x32_bf16 v[86:89], v[198:201], v[182:185], v[86:89]
	v_mfma_f32_16x16x32_bf16 v[82:85], v[206:209], v[182:185], v[82:85]
	v_mfma_f32_16x16x32_bf16 v[70:73], v[198:201], v[190:193], v[70:73]
	v_mfma_f32_16x16x32_bf16 v[66:69], v[206:209], v[190:193], v[66:69]
	s_mov_b32 m0, s17
	s_add_u32 s48, s24, 0x80
	s_addc_u32 s49, s25, 0
	s_barrier
	ds_read_b128 v[162:165], v145 offset:16384
	ds_read_b128 v[166:169], v145 offset:17408
	ds_read_b128 v[170:173], v145 offset:18432
	ds_read_b128 v[174:177], v145 offset:19456
	ds_read_b128 v[178:181], v145 offset:20480
	ds_read_b128 v[182:185], v145 offset:21504
	ds_read_b128 v[186:189], v145 offset:22528
	ds_read_b128 v[190:193], v145 offset:23552
	global_load_lds_dwordx4 v134, s[24:25]
	s_mov_b32 m0, s19
	s_nop 0
	global_load_lds_dwordx4 v132, s[24:25]
	s_barrier
	s_waitcnt lgkmcnt(0)
	v_mfma_f32_16x16x32_bf16 v[62:65], v[146:149], v[162:165], v[62:65]
	v_mfma_f32_16x16x32_bf16 v[58:61], v[154:157], v[162:165], v[58:61]
	v_mfma_f32_16x16x32_bf16 v[46:49], v[146:149], v[170:173], v[46:49]
	v_mfma_f32_16x16x32_bf16 v[42:45], v[154:157], v[170:173], v[42:45]
	v_mfma_f32_16x16x32_bf16 v[30:33], v[146:149], v[178:181], v[30:33]
	v_mfma_f32_16x16x32_bf16 v[26:29], v[154:157], v[178:181], v[26:29]
	v_mfma_f32_16x16x32_bf16 v[14:17], v[146:149], v[186:189], v[14:17]
	v_mfma_f32_16x16x32_bf16 v[10:13], v[154:157], v[186:189], v[10:13]
	v_mfma_f32_16x16x32_bf16 v[62:65], v[150:153], v[166:169], v[62:65]
	v_mfma_f32_16x16x32_bf16 v[58:61], v[158:161], v[166:169], v[58:61]
	v_mfma_f32_16x16x32_bf16 v[46:49], v[150:153], v[174:177], v[46:49]
	v_mfma_f32_16x16x32_bf16 v[42:45], v[158:161], v[174:177], v[42:45]
	v_mfma_f32_16x16x32_bf16 v[30:33], v[150:153], v[182:185], v[30:33]
	v_mfma_f32_16x16x32_bf16 v[26:29], v[158:161], v[182:185], v[26:29]
	v_mfma_f32_16x16x32_bf16 v[14:17], v[150:153], v[190:193], v[14:17]
	v_mfma_f32_16x16x32_bf16 v[10:13], v[158:161], v[190:193], v[10:13]
	s_barrier
	s_add_u32 s44, s22, 0x80000
	s_addc_u32 s45, s23, 0
	s_add_i32 s46, s46, s30
	s_mov_b32 m0, s46
	s_nop 0
	global_load_lds_dwordx4 v0, s[44:45]
	s_add_i32 m0, s46, 0x2000
	s_nop 0
	global_load_lds_dwordx4 v130, s[44:45]
	s_waitcnt vmcnt(6)
	s_barrier
; #define PG8_STAGE(bufoff, gbase, voff) do { _Pragma("unroll") for (int _i = 0; _i < 2; ++_i) \
;         __builtin_amdgcn_global_load_lds((const unsigned*)((const char*)(gbase) + (voff)[_i]), (LAS unsigned*)(lds + (bufoff) + ldsw + _i * 8192), 16, 0, 0); } while (0)
; #define PG8_LDA(dst, b, h) do { _Pragma("unroll") for (int m = 0; m < 4; ++m) _Pragma("unroll") for (int k = 0; k < 2; ++k) dst[m][k] = *(const LAS bf16x8*)(lds + PG8_SA(b, h) + aoff + m * 2048 + k * 1024); } while (0)
; #define PG8_LDB(dst, b, h) do { _Pragma("unroll") for (int n = 0; n < 2; ++n) _Pragma("unroll") for (int k = 0; k < 2; ++k) dst[n][k] = *(const LAS bf16x8*)(lds + PG8_SB(b, h) + boff + n * 2048 + k * 1024); } while (0)
; #define PG8_MMA(ai, bj, At, Bt) do { __builtin_amdgcn_s_setprio(1); _Pragma("unroll") for (int m = 0; m < 4; ++m) _Pragma("unroll") for (int n = 0; n < 2; ++n) _Pragma("unroll") for (int k = 0; k < 2; ++k) \
;         acc[ai][bj][m][n] = __builtin_amdgcn_mfma_f32_16x16x32_bf16(Bt[n][k], At[m][k], acc[ai][bj][m][n], 0, 0, 0); __builtin_amdgcn_s_setprio(0); } while (0)
; #define PG8_WAIT_V(n) asm volatile("s_waitcnt vmcnt(" #n ")" ::: "memory")
; #define PG8_WAIT_L(n) asm volatile("s_waitcnt lgkmcnt(" #n ")" ::: "memory")
; #define PG8_BAR __builtin_amdgcn_s_barrier()
; #define PG8_SCHED __builtin_amdgcn_sched_barrier(0)
; template <class Epi, class Sched>
; __device__ __forceinline__ void gemm_phase(LAS unsigned char* lds, const Gemm g, const Sched& S, const Epi& E) {
;     ...
;             PG8_WAIT_V(6); PG8_BAR; PG8_MMA(1, 1, At, B1); PG8_BAR;
;             PG8_LDB(B0, 1, 0); PG8_SCHED; PG8_LDA(At, 1, 0); PG8_STAGE(PG8_SA(0, 1), a2 + hstep, voffA);
;             PG8_WAIT_L(8); PG8_BAR; PG8_WAIT_L(0); PG8_MMA(0, 0, At, B0); PG8_BAR; PG8_SCHED;
;             PG8_LDB(B1, 1, 1); PG8_STAGE(PG8_SB(1, 0), b3, voffB);
;             PG8_BAR; PG8_WAIT_L(0); PG8_MMA(0, 1, At, B1); PG8_BAR;
;             PG8_LDA(At, 1, 1); PG8_STAGE(PG8_SA(1, 0), a3, voffA);
	v_mfma_f32_16x16x32_bf16 v[54:57], v[194:197], v[162:165], v[54:57]
	v_mfma_f32_16x16x32_bf16 v[50:53], v[202:205], v[162:165], v[50:53]
	v_mfma_f32_16x16x32_bf16 v[38:41], v[194:197], v[170:173], v[38:41]
	v_mfma_f32_16x16x32_bf16 v[34:37], v[202:205], v[170:173], v[34:37]
	v_mfma_f32_16x16x32_bf16 v[22:25], v[194:197], v[178:181], v[22:25]
	v_mfma_f32_16x16x32_bf16 v[18:21], v[202:205], v[178:181], v[18:21]
	v_mfma_f32_16x16x32_bf16 v[6:9], v[194:197], v[186:189], v[6:9]
	v_mfma_f32_16x16x32_bf16 v[2:5], v[202:205], v[186:189], v[2:5]
	v_mfma_f32_16x16x32_bf16 v[54:57], v[198:201], v[166:169], v[54:57]
	v_mfma_f32_16x16x32_bf16 v[50:53], v[206:209], v[166:169], v[50:53]
	v_mfma_f32_16x16x32_bf16 v[38:41], v[198:201], v[174:177], v[38:41]
	v_mfma_f32_16x16x32_bf16 v[34:37], v[206:209], v[174:177], v[34:37]
	v_mfma_f32_16x16x32_bf16 v[22:25], v[198:201], v[182:185], v[22:25]
	v_mfma_f32_16x16x32_bf16 v[18:21], v[206:209], v[182:185], v[18:21]
	v_mfma_f32_16x16x32_bf16 v[6:9], v[198:201], v[190:193], v[6:9]
	v_mfma_f32_16x16x32_bf16 v[2:5], v[206:209], v[190:193], v[2:5]
	s_add_i32 s44, 0, 0x18000
	s_barrier
	ds_read_b128 v[146:149], v220
	ds_read_b128 v[150:153], v220 offset:1024
	ds_read_b128 v[154:157], v220 offset:2048
	ds_read_b128 v[158:161], v220 offset:3072
	s_add_u32 s24, s24, 0x80000
	s_addc_u32 s25, s25, 0
	s_mov_b32 m0, s35
	ds_read_b128 v[162:165], v145 offset:32768
	ds_read_b128 v[166:169], v145 offset:33792
	ds_read_b128 v[170:173], v145 offset:34816
	ds_read_b128 v[174:177], v145 offset:35840
	ds_read_b128 v[178:181], v145 offset:36864
	ds_read_b128 v[182:185], v145 offset:37888
	ds_read_b128 v[186:189], v145 offset:38912
	ds_read_b128 v[190:193], v145 offset:39936
	global_load_lds_dwordx4 v134, s[24:25]
	s_mov_b32 m0, s36
	s_nop 0
	global_load_lds_dwordx4 v132, s[24:25]
	s_waitcnt lgkmcnt(8)
	s_barrier
	s_waitcnt lgkmcnt(0)
	v_mfma_f32_16x16x32_bf16 v[126:129], v[146:149], v[162:165], v[126:129]
	v_mfma_f32_16x16x32_bf16 v[122:125], v[154:157], v[162:165], v[122:125]
	v_mfma_f32_16x16x32_bf16 v[110:113], v[146:149], v[170:173], v[110:113]
	v_mfma_f32_16x16x32_bf16 v[106:109], v[154:157], v[170:173], v[106:109]
	v_mfma_f32_16x16x32_bf16 v[94:97], v[146:149], v[178:181], v[94:97]
	v_mfma_f32_16x16x32_bf16 v[90:93], v[154:157], v[178:181], v[90:93]
	v_mfma_f32_16x16x32_bf16 v[78:81], v[146:149], v[186:189], v[78:81]
	v_mfma_f32_16x16x32_bf16 v[74:77], v[154:157], v[186:189], v[74:77]
	v_mfma_f32_16x16x32_bf16 v[126:129], v[150:153], v[166:169], v[126:129]
	v_mfma_f32_16x16x32_bf16 v[122:125], v[158:161], v[166:169], v[122:125]
	v_mfma_f32_16x16x32_bf16 v[110:113], v[150:153], v[174:177], v[110:113]
	v_mfma_f32_16x16x32_bf16 v[106:109], v[158:161], v[174:177], v[106:109]
	v_mfma_f32_16x16x32_bf16 v[94:97], v[150:153], v[182:185], v[94:97]
	v_mfma_f32_16x16x32_bf16 v[90:93], v[158:161], v[182:185], v[90:93]
	v_mfma_f32_16x16x32_bf16 v[78:81], v[150:153], v[190:193], v[78:81]
	v_mfma_f32_16x16x32_bf16 v[74:77], v[158:161], v[190:193], v[74:77]
	s_barrier
	s_add_i32 s24, 0, 0x1c000
	s_add_i32 s25, s44, s30
	s_add_u32 s44, s22, 0x80
	s_addc_u32 s45, s23, 0
	s_mov_b32 m0, s25
	ds_read_b128 v[194:197], v221
	ds_read_b128 v[198:201], v221 offset:1024
	ds_read_b128 v[202:205], v221 offset:2048
	ds_read_b128 v[206:209], v221 offset:3072
	global_load_lds_dwordx4 v0, s[44:45]
	s_add_i32 m0, s25, 0x2000
	s_nop 0
	global_load_lds_dwordx4 v130, s[44:45]
	s_barrier
	s_waitcnt lgkmcnt(0)
	v_mfma_f32_16x16x32_bf16 v[118:121], v[194:197], v[162:165], v[118:121]
	v_mfma_f32_16x16x32_bf16 v[114:117], v[202:205], v[162:165], v[114:117]
	v_mfma_f32_16x16x32_bf16 v[102:105], v[194:197], v[170:173], v[102:105]
	v_mfma_f32_16x16x32_bf16 v[98:101], v[202:205], v[170:173], v[98:101]
	v_mfma_f32_16x16x32_bf16 v[86:89], v[194:197], v[178:181], v[86:89]
	v_mfma_f32_16x16x32_bf16 v[82:85], v[202:205], v[178:181], v[82:85]
	v_mfma_f32_16x16x32_bf16 v[70:73], v[194:197], v[186:189], v[70:73]
	v_mfma_f32_16x16x32_bf16 v[66:69], v[202:205], v[186:189], v[66:69]
	v_mfma_f32_16x16x32_bf16 v[118:121], v[198:201], v[166:169], v[118:121]
	v_mfma_f32_16x16x32_bf16 v[114:117], v[206:209], v[166:169], v[114:117]
	v_mfma_f32_16x16x32_bf16 v[102:105], v[198:201], v[174:177], v[102:105]
	v_mfma_f32_16x16x32_bf16 v[98:101], v[206:209], v[174:177], v[98:101]
	v_mfma_f32_16x16x32_bf16 v[86:89], v[198:201], v[182:185], v[86:89]
	v_mfma_f32_16x16x32_bf16 v[82:85], v[206:209], v[182:185], v[82:85]
	v_mfma_f32_16x16x32_bf16 v[70:73], v[198:201], v[190:193], v[70:73]
	v_mfma_f32_16x16x32_bf16 v[66:69], v[206:209], v[190:193], v[66:69]
	s_mov_b32 m0, s37
	s_barrier
	ds_read_b128 v[162:165], v145 offset:49152
	ds_read_b128 v[166:169], v145 offset:50176
	ds_read_b128 v[170:173], v145 offset:51200
	ds_read_b128 v[174:177], v145 offset:52224
	ds_read_b128 v[178:181], v145 offset:53248
	ds_read_b128 v[182:185], v145 offset:54272
	ds_read_b128 v[186:189], v145 offset:55296
	ds_read_b128 v[190:193], v145 offset:56320
	global_load_lds_dwordx4 v134, s[48:49]
	s_mov_b32 m0, s38
	s_nop 0
	global_load_lds_dwordx4 v132, s[48:49]
	s_barrier
; __device__ __forceinline__ unsigned cvt_pk_bf16(float lo, float hi) { f32x2_t v = {lo, hi}; bf16x2_t b = __builtin_convertvector(v, bf16x2_t); return __builtin_bit_cast(unsigned, b); }
; #define PG8_STAGE(bufoff, gbase, voff) do { _Pragma("unroll") for (int _i = 0; _i < 2; ++_i) \
;         __builtin_amdgcn_global_load_lds((const unsigned*)((const char*)(gbase) + (voff)[_i]), (LAS unsigned*)(lds + (bufoff) + ldsw + _i * 8192), 16, 0, 0); } while (0)
; #define PG8_MMA(ai, bj, At, Bt) do { __builtin_amdgcn_s_setprio(1); _Pragma("unroll") for (int m = 0; m < 4; ++m) _Pragma("unroll") for (int n = 0; n < 2; ++n) _Pragma("unroll") for (int k = 0; k < 2; ++k) \
;         acc[ai][bj][m][n] = __builtin_amdgcn_mfma_f32_16x16x32_bf16(Bt[n][k], At[m][k], acc[ai][bj][m][n], 0, 0, 0); __builtin_amdgcn_s_setprio(0); } while (0)
; #define PG8_WAIT_V(n) asm volatile("s_waitcnt vmcnt(" #n ")" ::: "memory")
; #define PG8_WAIT_L(n) asm volatile("s_waitcnt lgkmcnt(" #n ")" ::: "memory")
; #define PG8_BAR __builtin_amdgcn_s_barrier()
; template <class Epi, class Sched>
; __device__ __forceinline__ void gemm_phase(LAS unsigned char* lds, const Gemm g, const Sched& S, const Epi& E) {
;     ...
;             PG8_BAR; PG8_WAIT_L(0); PG8_MMA(1, 0, At, B0); PG8_BAR; PG8_SCHED;
;             PG8_STAGE(PG8_SB(1, 1), b3 + hstep, voffB);
;             PG8_WAIT_V(6); PG8_BAR; PG8_MMA(1, 1, At, B1); PG8_BAR;
;     __device__ __forceinline__ void operator()(const f32x4 (&acc)[2][2][4][2], const pg8::Unit& u, int wr, int wc, int fr, int fq) const {
;     ...
;             for (int m = 0; m < 4; ++m) { const int row = row0 + ai * 128 + m * 16; bf16_t* rowp = O + (size_t)row * ldc + col0;
; #pragma unroll
;                 for (int bj = 0; bj < 2; ++bj) { f32x4 v0 = acc[ai][bj][m][0], v1 = acc[ai][bj][m][1];
;                     if (ACT == 1) {
; #pragma unroll
;                         for (int j = 0; j < 4; ++j) { float a = fmaxf(v0[j], 0.f), b = fmaxf(v1[j], 0.f); v0[j] = a * a; v1[j] = b * b; } }
;                     if (ACT == 0) { if (u.pn == (C_G / 256) && bj == 0 && wc == 0 && fq < 2) { float* gp = gate + (size_t)row * 16 + 8 * fq; *(f32x4*)gp = v0; *(f32x4*)(gp + 4) = v1; } }
;                     u32x4 w; w.x = cvt_pk_bf16(v0[0], v0[1]); w.y = cvt_pk_bf16(v0[2], v0[3]); w.z = cvt_pk_bf16(v1[0], v1[1]); w.w = cvt_pk_bf16(v1[2], v1[3]);
;                     *(u32x4*)(rowp + bj * 128) = w; } }
	s_waitcnt lgkmcnt(0)
	v_mfma_f32_16x16x32_bf16 v[62:65], v[146:149], v[162:165], v[62:65]
	v_mfma_f32_16x16x32_bf16 v[58:61], v[154:157], v[162:165], v[58:61]
	v_mfma_f32_16x16x32_bf16 v[46:49], v[146:149], v[170:173], v[46:49]
	v_mfma_f32_16x16x32_bf16 v[42:45], v[154:157], v[170:173], v[42:45]
	v_mfma_f32_16x16x32_bf16 v[30:33], v[146:149], v[178:181], v[30:33]
	v_mfma_f32_16x16x32_bf16 v[26:29], v[154:157], v[178:181], v[26:29]
	v_mfma_f32_16x16x32_bf16 v[14:17], v[146:149], v[186:189], v[14:17]
	v_mfma_f32_16x16x32_bf16 v[10:13], v[154:157], v[186:189], v[10:13]
	v_mfma_f32_16x16x32_bf16 v[62:65], v[150:153], v[166:169], v[62:65]
	v_mfma_f32_16x16x32_bf16 v[58:61], v[158:161], v[166:169], v[58:61]
	v_mfma_f32_16x16x32_bf16 v[46:49], v[150:153], v[174:177], v[46:49]
	v_mfma_f32_16x16x32_bf16 v[42:45], v[158:161], v[174:177], v[42:45]
	v_mfma_f32_16x16x32_bf16 v[30:33], v[150:153], v[182:185], v[30:33]
	v_mfma_f32_16x16x32_bf16 v[26:29], v[158:161], v[182:185], v[26:29]
	v_mfma_f32_16x16x32_bf16 v[14:17], v[150:153], v[190:193], v[14:17]
	v_mfma_f32_16x16x32_bf16 v[10:13], v[158:161], v[190:193], v[10:13]
	s_barrier
	s_add_u32 s22, s22, 0x80080
	s_addc_u32 s23, s23, 0
	s_add_i32 s24, s24, s30
	s_mov_b32 m0, s24
	s_nop 0
	global_load_lds_dwordx4 v0, s[22:23]
	s_add_i32 m0, s24, 0x2000
	s_nop 0
	global_load_lds_dwordx4 v130, s[22:23]
	s_waitcnt vmcnt(6)
	s_barrier
	v_mfma_f32_16x16x32_bf16 v[54:57], v[194:197], v[162:165], v[54:57]
	v_mfma_f32_16x16x32_bf16 v[50:53], v[202:205], v[162:165], v[50:53]
	v_mfma_f32_16x16x32_bf16 v[38:41], v[194:197], v[170:173], v[38:41]
	v_mfma_f32_16x16x32_bf16 v[34:37], v[202:205], v[170:173], v[34:37]
	v_mfma_f32_16x16x32_bf16 v[22:25], v[194:197], v[178:181], v[22:25]
	v_mfma_f32_16x16x32_bf16 v[18:21], v[202:205], v[178:181], v[18:21]
	v_mfma_f32_16x16x32_bf16 v[6:9], v[194:197], v[186:189], v[6:9]
	v_mfma_f32_16x16x32_bf16 v[2:5], v[202:205], v[186:189], v[2:5]
	v_mfma_f32_16x16x32_bf16 v[54:57], v[198:201], v[166:169], v[54:57]
	v_mfma_f32_16x16x32_bf16 v[50:53], v[206:209], v[166:169], v[50:53]
	v_mfma_f32_16x16x32_bf16 v[38:41], v[198:201], v[174:177], v[38:41]
	v_mfma_f32_16x16x32_bf16 v[34:37], v[206:209], v[174:177], v[34:37]
	v_mfma_f32_16x16x32_bf16 v[22:25], v[198:201], v[182:185], v[22:25]
	v_mfma_f32_16x16x32_bf16 v[18:21], v[206:209], v[182:185], v[18:21]
	v_mfma_f32_16x16x32_bf16 v[6:9], v[198:201], v[190:193], v[6:9]
	v_mfma_f32_16x16x32_bf16 v[2:5], v[206:209], v[190:193], v[2:5]
	s_add_i32 s43, s43, 2
	s_add_u32 s20, s20, 0x100
	s_addc_u32 s21, s21, 0
	s_add_u32 s41, s41, 0x100
	s_addc_u32 s42, s42, 0
	s_cmp_gt_u32 s43, 29
	s_barrier
	s_cbranch_scc0 .LBB0_1279
	v_lshl_add_u32 v146, s18, 8, v142
	v_lshl_or_b32 v140, s16, 8, v144
	v_ashrrev_i32_e32 v147, 31, v146
	v_ashrrev_i32_e32 v141, 31, v140
	v_lshlrev_b64 v[148:149], 14, v[146:147]
	v_lshl_add_u64 v[148:149], s[58:59], 0, v[148:149]
	v_lshlrev_b64 v[150:151], 1, v[140:141]
	v_max_f32_e32 v122, 0, v122
	v_max_f32_e32 v123, 0, v123
	v_lshl_add_u64 v[140:141], v[148:149], 0, v[150:151]
	v_pk_mul_f32 v[148:149], v[122:123], v[122:123]
	v_max_f32_e32 v124, 0, v124
	v_max_f32_e32 v126, 0, v126
	v_max_f32_e32 v127, 0, v127
	v_max_f32_e32 v122, 0, v128
	v_max_f32_e32 v123, 0, v129
	v_max_f32_e32 v125, 0, v125
	v_pk_mul_f32 v[126:127], v[126:127], v[126:127]
	v_pk_mul_f32 v[128:129], v[122:123], v[122:123]
	v_pk_mul_f32 v[152:153], v[124:125], v[124:125]
	v_cvt_pk_bf16_f32 v122, v126, v127
	v_cvt_pk_bf16_f32 v123, v128, v129
	v_cvt_pk_bf16_f32 v124, v148, v149
	v_cvt_pk_bf16_f32 v125, v152, v153
	v_max_f32_e32 v114, 0, v114
	v_max_f32_e32 v115, 0, v115
	global_store_dwordx4 v[140:141], v[122:125], off
	s_nop 1
	v_pk_mul_f32 v[122:123], v[114:115], v[114:115]
	v_max_f32_e32 v116, 0, v116
	v_max_f32_e32 v118, 0, v118
	v_max_f32_e32 v119, 0, v119
	v_max_f32_e32 v114, 0, v120
	v_max_f32_e32 v115, 0, v121
	v_max_f32_e32 v117, 0, v117
	v_pk_mul_f32 v[118:119], v[118:119], v[118:119]
	v_pk_mul_f32 v[120:121], v[114:115], v[114:115]
	v_pk_mul_f32 v[124:125], v[116:117], v[116:117]
	v_cvt_pk_bf16_f32 v114, v118, v119
	v_cvt_pk_bf16_f32 v115, v120, v121
	v_cvt_pk_bf16_f32 v116, v122, v123
	v_cvt_pk_bf16_f32 v117, v124, v125
	v_max_f32_e32 v106, 0, v106
	v_max_f32_e32 v107, 0, v107
	global_store_dwordx4 v[140:141], v[114:117], off offset:256
	s_nop 1
	v_or_b32_e32 v114, 16, v146
	v_pk_mul_f32 v[116:117], v[106:107], v[106:107]
	v_ashrrev_i32_e32 v115, 31, v114
	v_max_f32_e32 v108, 0, v108
	v_lshlrev_b64 v[114:115], 14, v[114:115]
	v_max_f32_e32 v110, 0, v110
	v_max_f32_e32 v111, 0, v111
	v_max_f32_e32 v106, 0, v112
	v_max_f32_e32 v107, 0, v113
	v_max_f32_e32 v109, 0, v109
	v_lshl_add_u64 v[114:115], s[58:59], 0, v[114:115]
	v_pk_mul_f32 v[110:111], v[110:111], v[110:111]
	v_pk_mul_f32 v[112:113], v[106:107], v[106:107]
	v_pk_mul_f32 v[118:119], v[108:109], v[108:109]
	v_lshl_add_u64 v[114:115], v[114:115], 0, v[150:151]
	v_cvt_pk_bf16_f32 v106, v110, v111
	v_cvt_pk_bf16_f32 v107, v112, v113
	v_cvt_pk_bf16_f32 v108, v116, v117
	v_cvt_pk_bf16_f32 v109, v118, v119
	v_max_f32_e32 v98, 0, v98
	v_max_f32_e32 v99, 0, v99
	global_store_dwordx4 v[114:115], v[106:109], off
	s_nop 1
	v_pk_mul_f32 v[106:107], v[98:99], v[98:99]
	v_max_f32_e32 v100, 0, v100
	v_max_f32_e32 v102, 0, v102
	v_max_f32_e32 v103, 0, v103
	v_max_f32_e32 v98, 0, v104
	v_max_f32_e32 v99, 0, v105
	v_max_f32_e32 v101, 0, v101
	v_pk_mul_f32 v[102:103], v[102:103], v[102:103]
	v_pk_mul_f32 v[104:105], v[98:99], v[98:99]
	v_pk_mul_f32 v[108:109], v[100:101], v[100:101]
	v_cvt_pk_bf16_f32 v98, v102, v103
	v_cvt_pk_bf16_f32 v99, v104, v105
	v_cvt_pk_bf16_f32 v100, v106, v107
; __device__ __forceinline__ unsigned cvt_pk_bf16(float lo, float hi) { f32x2_t v = {lo, hi}; bf16x2_t b = __builtin_convertvector(v, bf16x2_t); return __builtin_bit_cast(unsigned, b); }
;     __device__ __forceinline__ void operator()(const f32x4 (&acc)[2][2][4][2], const pg8::Unit& u, int wr, int wc, int fr, int fq) const {
;     ...
;             for (int m = 0; m < 4; ++m) { const int row = row0 + ai * 128 + m * 16; bf16_t* rowp = O + (size_t)row * ldc + col0;
; #pragma unroll
;                 for (int bj = 0; bj < 2; ++bj) { f32x4 v0 = acc[ai][bj][m][0], v1 = acc[ai][bj][m][1];
;                     if (ACT == 1) {
; #pragma unroll
;                         for (int j = 0; j < 4; ++j) { float a = fmaxf(v0[j], 0.f), b = fmaxf(v1[j], 0.f); v0[j] = a * a; v1[j] = b * b; } }
;                     if (ACT == 0) { if (u.pn == (C_G / 256) && bj == 0 && wc == 0 && fq < 2) { float* gp = gate + (size_t)row * 16 + 8 * fq; *(f32x4*)gp = v0; *(f32x4*)(gp + 4) = v1; } }
;                     u32x4 w; w.x = cvt_pk_bf16(v0[0], v0[1]); w.y = cvt_pk_bf16(v0[2], v0[3]); w.z = cvt_pk_bf16(v1[0], v1[1]); w.w = cvt_pk_bf16(v1[2], v1[3]);
;                     *(u32x4*)(rowp + bj * 128) = w; } }
	v_cvt_pk_bf16_f32 v101, v108, v109
	v_max_f32_e32 v90, 0, v90
	v_max_f32_e32 v91, 0, v91
	global_store_dwordx4 v[114:115], v[98:101], off offset:256
	s_nop 1
	v_or_b32_e32 v98, 32, v146
	v_pk_mul_f32 v[100:101], v[90:91], v[90:91]
	v_ashrrev_i32_e32 v99, 31, v98
	v_max_f32_e32 v92, 0, v92
	v_lshlrev_b64 v[98:99], 14, v[98:99]
	v_max_f32_e32 v94, 0, v94
	v_max_f32_e32 v95, 0, v95
	v_max_f32_e32 v90, 0, v96
	v_max_f32_e32 v91, 0, v97
	v_max_f32_e32 v93, 0, v93
	v_lshl_add_u64 v[98:99], s[58:59], 0, v[98:99]
	v_pk_mul_f32 v[94:95], v[94:95], v[94:95]
	v_pk_mul_f32 v[96:97], v[90:91], v[90:91]
	v_pk_mul_f32 v[102:103], v[92:93], v[92:93]
	v_lshl_add_u64 v[98:99], v[98:99], 0, v[150:151]
	v_cvt_pk_bf16_f32 v90, v94, v95
	v_cvt_pk_bf16_f32 v91, v96, v97
	v_cvt_pk_bf16_f32 v92, v100, v101
	v_cvt_pk_bf16_f32 v93, v102, v103
	v_max_f32_e32 v82, 0, v82
	v_max_f32_e32 v83, 0, v83
	global_store_dwordx4 v[98:99], v[90:93], off
	s_nop 1
	v_pk_mul_f32 v[90:91], v[82:83], v[82:83]
	v_max_f32_e32 v84, 0, v84
	v_max_f32_e32 v86, 0, v86
	v_max_f32_e32 v87, 0, v87
	v_max_f32_e32 v82, 0, v88
	v_max_f32_e32 v83, 0, v89
	v_max_f32_e32 v85, 0, v85
	v_pk_mul_f32 v[86:87], v[86:87], v[86:87]
	v_pk_mul_f32 v[88:89], v[82:83], v[82:83]
	v_pk_mul_f32 v[92:93], v[84:85], v[84:85]
	v_cvt_pk_bf16_f32 v82, v86, v87
	v_cvt_pk_bf16_f32 v83, v88, v89
	v_cvt_pk_bf16_f32 v84, v90, v91
	v_cvt_pk_bf16_f32 v85, v92, v93
	v_max_f32_e32 v74, 0, v74
	v_max_f32_e32 v75, 0, v75
	global_store_dwordx4 v[98:99], v[82:85], off offset:256
	s_nop 1
	v_or_b32_e32 v82, 48, v146
	v_pk_mul_f32 v[84:85], v[74:75], v[74:75]
	v_ashrrev_i32_e32 v83, 31, v82
	v_max_f32_e32 v76, 0, v76
	v_lshlrev_b64 v[82:83], 14, v[82:83]
	v_max_f32_e32 v78, 0, v78
	v_max_f32_e32 v79, 0, v79
	v_max_f32_e32 v74, 0, v80
	v_max_f32_e32 v75, 0, v81
	v_max_f32_e32 v77, 0, v77
	v_lshl_add_u64 v[82:83], s[58:59], 0, v[82:83]
	v_pk_mul_f32 v[78:79], v[78:79], v[78:79]
	v_pk_mul_f32 v[80:81], v[74:75], v[74:75]
	v_pk_mul_f32 v[86:87], v[76:77], v[76:77]
	v_lshl_add_u64 v[82:83], v[82:83], 0, v[150:151]
	v_cvt_pk_bf16_f32 v74, v78, v79
	v_cvt_pk_bf16_f32 v75, v80, v81
	v_cvt_pk_bf16_f32 v76, v84, v85
	v_cvt_pk_bf16_f32 v77, v86, v87
	v_max_f32_e32 v66, 0, v66
	v_max_f32_e32 v67, 0, v67
	global_store_dwordx4 v[82:83], v[74:77], off
	s_nop 1
	v_pk_mul_f32 v[74:75], v[66:67], v[66:67]
	v_max_f32_e32 v68, 0, v68
	v_max_f32_e32 v70, 0, v70
	v_max_f32_e32 v71, 0, v71
	v_max_f32_e32 v66, 0, v72
	v_max_f32_e32 v67, 0, v73
	v_max_f32_e32 v69, 0, v69
	v_pk_mul_f32 v[70:71], v[70:71], v[70:71]
	v_pk_mul_f32 v[72:73], v[66:67], v[66:67]
	v_pk_mul_f32 v[76:77], v[68:69], v[68:69]
	v_cvt_pk_bf16_f32 v66, v70, v71
	v_cvt_pk_bf16_f32 v67, v72, v73
	v_cvt_pk_bf16_f32 v68, v74, v75
	v_cvt_pk_bf16_f32 v69, v76, v77
	v_max_f32_e32 v58, 0, v58
	v_max_f32_e32 v59, 0, v59
	global_store_dwordx4 v[82:83], v[66:69], off offset:256
	s_nop 1
	v_pk_mul_f32 v[68:69], v[58:59], v[58:59]
	v_max_f32_e32 v62, 0, v62
	v_max_f32_e32 v63, 0, v63
	v_max_f32_e32 v60, 0, v60
	v_pk_mul_f32 v[62:63], v[62:63], v[62:63]
	v_max_f32_e32 v58, 0, v64
	v_max_f32_e32 v59, 0, v65
	v_max_f32_e32 v61, 0, v61
	s_mov_b32 s3, 0x200000
	v_pk_mul_f32 v[64:65], v[58:59], v[58:59]
	v_pk_mul_f32 v[70:71], v[60:61], v[60:61]
	v_cvt_pk_bf16_f32 v58, v62, v63
	v_add_co_u32_e32 v62, vcc, s3, v140
	v_cvt_pk_bf16_f32 v59, v64, v65
	v_cvt_pk_bf16_f32 v60, v68, v69
	v_cvt_pk_bf16_f32 v61, v70, v71
	v_addc_co_u32_e32 v63, vcc, 0, v141, vcc
	v_max_f32_e32 v50, 0, v50
	v_max_f32_e32 v51, 0, v51
	global_store_dwordx4 v[62:63], v[58:61], off
	s_nop 1
	v_pk_mul_f32 v[58:59], v[50:51], v[50:51]
	v_max_f32_e32 v52, 0, v52
	v_max_f32_e32 v54, 0, v54
	v_max_f32_e32 v55, 0, v55
	v_max_f32_e32 v50, 0, v56
	v_max_f32_e32 v51, 0, v57
	v_max_f32_e32 v53, 0, v53
	s_mov_b64 s[20:21], 0x200000
	v_pk_mul_f32 v[54:55], v[54:55], v[54:55]
	v_pk_mul_f32 v[56:57], v[50:51], v[50:51]
	v_pk_mul_f32 v[60:61], v[52:53], v[52:53]
	v_lshl_add_u64 v[66:67], v[140:141], 0, s[20:21]
	v_cvt_pk_bf16_f32 v50, v54, v55
	v_cvt_pk_bf16_f32 v51, v56, v57
	v_cvt_pk_bf16_f32 v52, v58, v59
	v_cvt_pk_bf16_f32 v53, v60, v61
	v_max_f32_e32 v42, 0, v42
	v_max_f32_e32 v43, 0, v43
	global_store_dwordx4 v[66:67], v[50:53], off offset:256
; __device__ __forceinline__ unsigned cvt_pk_bf16(float lo, float hi) { f32x2_t v = {lo, hi}; bf16x2_t b = __builtin_convertvector(v, bf16x2_t); return __builtin_bit_cast(unsigned, b); }
; #define PG8_WAIT_V(n) asm volatile("s_waitcnt vmcnt(" #n ")" ::: "memory")
; #define PG8_BAR __builtin_amdgcn_s_barrier()
; template <class Epi, class Sched>
; __device__ __forceinline__ void gemm_phase(LAS unsigned char* lds, const Gemm g, const Sched& S, const Epi& E) {
;     ...
;         E(acc, cur, wr, wc, fr, fq); S.done(cur);
;         if (!has_next) break;
; #pragma unroll
;         for (int a = 0; a < 2; ++a)
; #pragma unroll
;             for (int b = 0; b < 2; ++b)
; #pragma unroll
;                 for (int m = 0; m < 4; ++m)
; #pragma unroll
;                     for (int n = 0; n < 2; ++n) acc[a][b][m][n] = (f32x4){0.f, 0.f, 0.f, 0.f};
;         cur = nxt; cA = nA; cB = nB; ++ui;
;     }
;     PG8_WAIT_V(0);
;     if (wr == 0) PG8_BAR;
;     PG8_BAR;
;     __device__ __forceinline__ void operator()(const f32x4 (&acc)[2][2][4][2], const pg8::Unit& u, int wr, int wc, int fr, int fq) const {
;     ...
;             for (int m = 0; m < 4; ++m) { const int row = row0 + ai * 128 + m * 16; bf16_t* rowp = O + (size_t)row * ldc + col0;
; #pragma unroll
;                 for (int bj = 0; bj < 2; ++bj) { f32x4 v0 = acc[ai][bj][m][0], v1 = acc[ai][bj][m][1];
;                     if (ACT == 1) {
; #pragma unroll
;                         for (int j = 0; j < 4; ++j) { float a = fmaxf(v0[j], 0.f), b = fmaxf(v1[j], 0.f); v0[j] = a * a; v1[j] = b * b; } }
;                     if (ACT == 0) { if (u.pn == (C_G / 256) && bj == 0 && wc == 0 && fq < 2) { float* gp = gate + (size_t)row * 16 + 8 * fq; *(f32x4*)gp = v0; *(f32x4*)(gp + 4) = v1; } }
;                     u32x4 w; w.x = cvt_pk_bf16(v0[0], v0[1]); w.y = cvt_pk_bf16(v0[2], v0[3]); w.z = cvt_pk_bf16(v1[0], v1[1]); w.w = cvt_pk_bf16(v1[2], v1[3]);
;                     *(u32x4*)(rowp + bj * 128) = w; } }
	s_nop 1
	v_pk_mul_f32 v[52:53], v[42:43], v[42:43]
	v_max_f32_e32 v46, 0, v46
	v_max_f32_e32 v47, 0, v47
	v_max_f32_e32 v44, 0, v44
	v_pk_mul_f32 v[46:47], v[46:47], v[46:47]
	v_max_f32_e32 v42, 0, v48
	v_max_f32_e32 v43, 0, v49
	v_max_f32_e32 v45, 0, v45
	s_mov_b32 s3, 0x240000
	v_pk_mul_f32 v[48:49], v[42:43], v[42:43]
	v_pk_mul_f32 v[54:55], v[44:45], v[44:45]
	v_cvt_pk_bf16_f32 v42, v46, v47
	v_add_co_u32_e32 v46, vcc, s3, v140
	v_cvt_pk_bf16_f32 v43, v48, v49
	v_cvt_pk_bf16_f32 v44, v52, v53
	v_cvt_pk_bf16_f32 v45, v54, v55
	v_addc_co_u32_e32 v47, vcc, 0, v141, vcc
	v_max_f32_e32 v34, 0, v34
	v_max_f32_e32 v35, 0, v35
	global_store_dwordx4 v[46:47], v[42:45], off
	s_nop 1
	v_pk_mul_f32 v[42:43], v[34:35], v[34:35]
	v_max_f32_e32 v36, 0, v36
	v_max_f32_e32 v38, 0, v38
	v_max_f32_e32 v39, 0, v39
	v_max_f32_e32 v34, 0, v40
	v_max_f32_e32 v35, 0, v41
	v_max_f32_e32 v37, 0, v37
	s_mov_b64 s[20:21], 0x240000
	v_pk_mul_f32 v[38:39], v[38:39], v[38:39]
	v_pk_mul_f32 v[40:41], v[34:35], v[34:35]
	v_pk_mul_f32 v[44:45], v[36:37], v[36:37]
	v_lshl_add_u64 v[50:51], v[140:141], 0, s[20:21]
	v_cvt_pk_bf16_f32 v34, v38, v39
	v_cvt_pk_bf16_f32 v35, v40, v41
	v_cvt_pk_bf16_f32 v36, v42, v43
	v_cvt_pk_bf16_f32 v37, v44, v45
	v_max_f32_e32 v26, 0, v26
	v_max_f32_e32 v27, 0, v27
	global_store_dwordx4 v[50:51], v[34:37], off offset:256
	s_nop 1
	v_pk_mul_f32 v[36:37], v[26:27], v[26:27]
	v_max_f32_e32 v30, 0, v30
	v_max_f32_e32 v31, 0, v31
	v_max_f32_e32 v28, 0, v28
	v_pk_mul_f32 v[30:31], v[30:31], v[30:31]
	v_max_f32_e32 v26, 0, v32
	v_max_f32_e32 v27, 0, v33
	v_max_f32_e32 v29, 0, v29
	s_mov_b32 s3, 0x280000
	v_pk_mul_f32 v[32:33], v[26:27], v[26:27]
	v_pk_mul_f32 v[38:39], v[28:29], v[28:29]
	v_cvt_pk_bf16_f32 v26, v30, v31
	v_add_co_u32_e32 v30, vcc, s3, v140
	v_cvt_pk_bf16_f32 v27, v32, v33
	v_cvt_pk_bf16_f32 v28, v36, v37
	v_cvt_pk_bf16_f32 v29, v38, v39
	v_addc_co_u32_e32 v31, vcc, 0, v141, vcc
	v_max_f32_e32 v18, 0, v18
	v_max_f32_e32 v19, 0, v19
	global_store_dwordx4 v[30:31], v[26:29], off
	s_nop 1
	v_pk_mul_f32 v[26:27], v[18:19], v[18:19]
	v_max_f32_e32 v20, 0, v20
	v_max_f32_e32 v22, 0, v22
	v_max_f32_e32 v23, 0, v23
	v_max_f32_e32 v18, 0, v24
	v_max_f32_e32 v19, 0, v25
	v_max_f32_e32 v21, 0, v21
	s_mov_b64 s[20:21], 0x280000
	v_pk_mul_f32 v[22:23], v[22:23], v[22:23]
	v_pk_mul_f32 v[24:25], v[18:19], v[18:19]
	v_pk_mul_f32 v[28:29], v[20:21], v[20:21]
	v_lshl_add_u64 v[34:35], v[140:141], 0, s[20:21]
	v_cvt_pk_bf16_f32 v18, v22, v23
	v_cvt_pk_bf16_f32 v19, v24, v25
	v_cvt_pk_bf16_f32 v20, v26, v27
	v_cvt_pk_bf16_f32 v21, v28, v29
	v_max_f32_e32 v10, 0, v10
	v_max_f32_e32 v11, 0, v11
	global_store_dwordx4 v[34:35], v[18:21], off offset:256
	s_nop 1
	v_pk_mul_f32 v[20:21], v[10:11], v[10:11]
	v_max_f32_e32 v14, 0, v14
	v_max_f32_e32 v15, 0, v15
	v_max_f32_e32 v12, 0, v12
	v_pk_mul_f32 v[14:15], v[14:15], v[14:15]
	v_max_f32_e32 v10, 0, v16
	v_max_f32_e32 v11, 0, v17
	v_max_f32_e32 v13, 0, v13
	s_mov_b32 s3, 0x2c0000
	v_pk_mul_f32 v[16:17], v[10:11], v[10:11]
	v_pk_mul_f32 v[22:23], v[12:13], v[12:13]
	v_cvt_pk_bf16_f32 v10, v14, v15
	v_add_co_u32_e32 v14, vcc, s3, v140
	v_cvt_pk_bf16_f32 v11, v16, v17
	v_cvt_pk_bf16_f32 v12, v20, v21
	v_cvt_pk_bf16_f32 v13, v22, v23
	v_addc_co_u32_e32 v15, vcc, 0, v141, vcc
	v_max_f32_e32 v2, 0, v2
	v_max_f32_e32 v3, 0, v3
	global_store_dwordx4 v[14:15], v[10:13], off
	s_nop 1
	v_pk_mul_f32 v[10:11], v[2:3], v[2:3]
	v_max_f32_e32 v4, 0, v4
	v_max_f32_e32 v6, 0, v6
	v_max_f32_e32 v7, 0, v7
	v_max_f32_e32 v2, 0, v8
	v_max_f32_e32 v3, 0, v9
	v_max_f32_e32 v5, 0, v5
	s_mov_b64 s[20:21], 0x2c0000
	v_pk_mul_f32 v[6:7], v[6:7], v[6:7]
	v_pk_mul_f32 v[8:9], v[2:3], v[2:3]
	v_pk_mul_f32 v[12:13], v[4:5], v[4:5]
	v_lshl_add_u64 v[18:19], v[140:141], 0, s[20:21]
	v_cvt_pk_bf16_f32 v2, v6, v7
	v_cvt_pk_bf16_f32 v3, v8, v9
	v_cvt_pk_bf16_f32 v4, v10, v11
	v_cvt_pk_bf16_f32 v5, v12, v13
	s_and_b64 vcc, exec, s[0:1]
	s_mov_b32 s16, s8
	s_mov_b32 s18, s10
	s_mov_b64 s[22:23], s[14:15]
	s_mov_b64 s[20:21], s[12:13]
	global_store_dwordx4 v[18:19], v[2:5], off offset:256
	s_nop 1
	s_cbranch_vccz .LBB0_1276
	s_waitcnt vmcnt(0)
	s_cmpk_gt_u32 s27, 0xff
	s_cbranch_scc1 .LBB0_1283
	s_barrier
